# scan: S8 consumer body + A/B in consumer with in-body stores/gate loads (AB3) + producer 16-byte q/k/decay loads restaged through LDS (R1)
# baseline (speedup 1.0000x reference)
.LBB0_280:
	s_or_b64 exec, exec, s[0:1]
	v_readlane_b32 s8, v251, 39
	v_readlane_b32 s9, v251, 40
	s_ashr_i32 s14, s15, 6
	v_and_b32_e32 v174, 63, v161
	v_cndmask_b32_e64 v1, 0, 1, s[8:9]
	v_and_b32_e32 v0, 15, v161
	v_bfe_u32 v47, v161, 4, 2
	s_mov_b64 s[0:1], -1
	s_cmp_lt_i32 s14, 4
	v_cmp_ne_u32_e64 s[38:39], 1, v1
	s_cbranch_scc1 .LBB0_312
	s_and_b64 vcc, exec, s[38:39]
	s_cbranch_vccnz .LBB0_311
	v_add_u32_e32 v53, 0xffffff00, v161
	v_ashrrev_i32_e32 v175, 3, v53
	s_movk_i32 s0, 0x410
	v_lshl_or_b32 v1, s14, 4, v0
	s_waitcnt lgkmcnt(0)
	v_mul_lo_u32 v3, v175, s0
	v_readlane_b32 s0, v254, 38
	s_waitcnt vmcnt(0)
	v_subrev_u32_e32 v6, 64, v1
	v_and_b32_e32 v1, 7, v161
	v_add_u32_e32 v7, s0, v3
	v_readlane_b32 s0, v253, 53
	v_lshlrev_b32_e32 v4, 3, v1
	v_mov_b32_e32 v5, v2
	v_readlane_b32 s1, v253, 54
	v_lshlrev_b32_e32 v176, 3, v47
	v_lshlrev_b32_e32 v9, 1, v161
	v_lshl_add_u64 v[36:37], s[0:1], 0, v[4:5]
	v_readlane_b32 s0, v251, 22
	v_readlane_b32 s1, v251, 23
	v_lshlrev_b32_e32 v8, 4, v1
	v_lshl_add_u32 v177, v53, 6, 0
	v_lshl_add_u64 v[38:39], s[0:1], 0, v[4:5]
	s_movk_i32 s0, 0xa0
	v_mul_lo_u32 v5, v6, s0
	s_movk_i32 s0, 0xff68
	v_add_u32_e32 v185, 0, v5
	v_mul_lo_u32 v186, v6, s0
	v_lshlrev_b32_e32 v4, 2, v6
	v_add_u32_e32 v187, v185, v186
	v_sub_u32_e32 v46, v187, v4
	s_movk_i32 s0, 0x9c
	v_or_b32_e32 v40, 2, v176
	v_or_b32_e32 v3, 3, v176
	v_or_b32_e32 v43, 4, v176
	v_or_b32_e32 v42, 5, v176
	v_or_b32_e32 v45, 6, v176
	v_or_b32_e32 v44, 7, v176
	v_and_b32_e32 v180, 24, v9
	v_bitop3_b32 v181, v9, 8, 24 bitop3:0x6c
	v_bitop3_b32 v182, v9, 16, 24 bitop3:0x6c
	v_bitop3_b32 v183, v9, 24, v9 bitop3:0xc
	v_add_u32_e32 v9, 0, v4
	v_mul_u32_u24_e32 v184, 0x840, v47
	v_mad_u64_u32 v[48:49], s[0:1], v6, s0, v[46:47]
	v_lshlrev_b32_e32 v55, 1, v6
	v_add_u32_e32 v178, 0xd800, v177
	v_cmp_gt_u32_e64 s[40:41], 16, v174
	v_cmp_lt_u32_e64 s[42:43], 31, v174
	v_and_b32_e32 v179, 48, v161
	v_or_b32_e32 v1, 1, v176
	v_pk_mov_b32 v[50:51], v[44:45], v[42:43] op_sel:[1,0]
	v_mov_b32_e32 v52, v43
	v_mov_b32_e32 v54, v3
	v_mov_b32_e32 v41, v40
	v_add_u32_e32 v49, v9, v184
	v_add_u32_e32 v188, v7, v8
	s_sub_i32 s98, s14, 4
	s_mul_i32 s99, s98, 0xa00
	s_add_i32 s99, s99, 0x4200
	v_mul_u32_u24_e32 v88, 0x240, v47
	v_add_u32_e32 v88, s99, v88
	v_lshl_add_u32 v180, v0, 4, v88
	v_lshl_add_u32 v181, v0, 2, v88
	v_lshl_add_u32 v182, v0, 3, v88
	v_lshrrev_b32_e32 v88, 2, v0
	v_lshl_add_u32 v88, v47, 3, v88
	v_lshlrev_b32_e32 v88, 12, v88
	v_and_b32_e32 v89, 3, v0
	v_lshl_add_u32 v88, v89, 4, v88
	s_lshl_b32 s99, s98, 6
	v_add_u32_e32 v177, s99, v88
	v_lshrrev_b32_e32 v88, 3, v0
	v_lshl_add_u32 v88, v47, 3, v88
	v_lshlrev_b32_e32 v88, 13, v88
	v_and_b32_e32 v89, 7, v0
	v_lshl_add_u32 v88, v89, 4, v88
	s_lshl_b32 s99, s98, 7
	v_add_u32_e32 v178, s99, v88
	s_mov_b32 s16, s2
	s_branch .LBB0_284
.LBB0_283:
	s_waitcnt vmcnt(0)
	v_readlane_b32 s0, v253, 61
	s_add_i32 s16, s16, s0
	s_cmpk_gt_i32 s16, 0x23f
	s_cbranch_scc1 .LBB0_311

.LBB0_288:
	s_add_i32 s0, s17, 31
	s_lshr_b32 s18, s0, 5
	s_add_i32 s0, s18, 3
	s_and_b32 s19, s0, 0x46
	s_cmp_eq_u32 s19, 0
	s_cbranch_scc1 .LBB0_283
	s_and_b32 s0, s16, 15
	s_mov_b32 s96, s8
	s_lshl_b32 s97, s0, 8
	s_add_i32 s20, s18, -1
	s_ashr_i32 s9, s8, 31
	s_cmp_eq_u32 s20, 0
	v_add_u32_e32 v56, s8, v176
	s_cselect_b32 s1, 0, 32
	s_waitcnt vmcnt(0)
	v_add_u32_e32 v20, s1, v56
	v_ashrrev_i32_e32 v21, 31, v20
	v_lshl_add_u32 v58, s0, 7, v55
	v_mov_b32_e32 v59, v2
	v_lshlrev_b64 v[20:21], 11, v[20:21]
	v_lshl_add_u64 v[20:21], v[20:21], 0, v[58:59]
	v_lshlrev_b64 v[22:23], 1, v[20:21]
	v_lshl_add_u64 v[24:25], s[72:73], 0, v[22:23]
	v_add_co_u32_e32 v26, vcc, s33, v24
	v_lshl_add_u64 v[22:23], s[64:65], 0, v[22:23]
	s_nop 0
	v_addc_co_u32_e32 v27, vcc, 0, v25, vcc
	v_add_co_u32_e32 v28, vcc, s33, v22
	v_lshl_add_u64 v[20:21], v[20:21], 2, s[74:75]
	s_nop 0
	v_addc_co_u32_e32 v29, vcc, 0, v23, vcc
	s_mov_b32 s3, 0xe000
	v_add_co_u32_e32 v30, vcc, s3, v20
	v_readlane_b32 s10, v251, 37
	s_nop 0
	v_addc_co_u32_e32 v31, vcc, 0, v21, vcc
	v_readlane_b32 s11, v251, 38
	v_add_co_u32_e32 v32, vcc, s63, v24
	v_lshl_add_u32 v6, s0, 8, v53
	v_mov_b64_e32 v[4:5], s[10:11]
	v_addc_co_u32_e32 v33, vcc, 0, v25, vcc
	v_mad_i64_i32 v[4:5], s[10:11], v6, s93, v[4:5]
	v_add_co_u32_e32 v34, vcc, s63, v22
	v_readlane_b32 s10, v253, 63
	s_nop 0
	v_addc_co_u32_e32 v35, vcc, 0, v23, vcc
	v_lshl_add_u64 v[60:61], s[8:9], 1, v[4:5]
	v_readlane_b32 s11, v254, 0
	s_lshl_b32 s10, s1, 1
	v_add_co_u32_e32 v62, vcc, s67, v20
	v_lshl_add_u64 v[16:17], v[60:61], 0, s[10:11]
	s_nop 0
	v_addc_co_u32_e32 v63, vcc, 0, v21, vcc
	s_movk_i32 s10, 0x5000
	s_nop 0
	s_nop 0
	global_load_dwordx2 v[64:65], v[30:31], off
	global_load_dword v196, v[32:33], off
	global_load_dword v189, v[34:35], off
	global_load_dwordx2 v[66:67], v[62:63], off
	v_add_co_u32_e32 v30, vcc, s10, v24
	s_mov_b32 s9, 0xa000
	s_nop 0
	v_addc_co_u32_e32 v31, vcc, 0, v25, vcc
	v_add_co_u32_e32 v32, vcc, s10, v22
	s_mov_b32 s1, 0x8000
	s_nop 0
	v_addc_co_u32_e32 v33, vcc, 0, v23, vcc
	v_add_co_u32_e32 v34, vcc, s9, v20
	s_movk_i32 s12, 0x3000
	s_nop 0
	v_addc_co_u32_e32 v35, vcc, 0, v21, vcc
	v_add_co_u32_e32 v68, vcc, s66, v24
	s_movk_i32 s13, 0x1000
	s_nop 0
	v_addc_co_u32_e32 v69, vcc, 0, v25, vcc
	v_add_co_u32_e32 v70, vcc, s66, v22
	v_ashrrev_i32_e32 v57, 31, v56
	s_nop 0
	v_addc_co_u32_e32 v71, vcc, 0, v23, vcc
	global_load_dword v198, v[30:31], off
	global_load_dword v192, v[32:33], off
	global_load_dwordx2 v[62:63], v[34:35], off
	global_load_dword v197, v[68:69], off
	global_load_dword v190, v[70:71], off
	v_add_co_u32_e32 v30, vcc, s1, v20
	v_lshlrev_b64 v[78:79], 11, v[56:57]
	s_nop 0
	v_addc_co_u32_e32 v31, vcc, 0, v21, vcc
	v_add_co_u32_e32 v32, vcc, s12, v24
	v_lshl_add_u64 v[78:79], v[78:79], 0, v[58:59]
	s_nop 0
	v_addc_co_u32_e32 v33, vcc, 0, v25, vcc
	v_add_co_u32_e32 v34, vcc, s12, v22
	v_lshlrev_b64 v[80:81], 1, v[78:79]
	s_nop 0
	v_addc_co_u32_e32 v35, vcc, 0, v23, vcc
	v_add_co_u32_e32 v68, vcc, s63, v20
	v_lshl_add_u64 v[82:83], s[72:73], 0, v[80:81]
	s_nop 0
	v_addc_co_u32_e32 v69, vcc, 0, v21, vcc
	global_load_dwordx2 v[70:71], v[30:31], off
	global_load_dword v200, v[32:33], off
	global_load_dword v191, v[34:35], off
	global_load_dwordx2 v[72:73], v[68:69], off
	v_add_co_u32_e32 v30, vcc, s69, v24
	v_lshl_add_u64 v[80:81], s[64:65], 0, v[80:81]
	s_nop 0
	v_addc_co_u32_e32 v31, vcc, 0, v25, vcc
	v_add_co_u32_e32 v32, vcc, s69, v22
	v_lshl_add_u64 v[78:79], v[78:79], 2, s[74:75]
	s_nop 0
	v_addc_co_u32_e32 v33, vcc, 0, v23, vcc
	v_add_co_u32_e32 v34, vcc, s66, v20
	v_xor_b32_e32 v57, 1, v208
	s_nop 0
	v_addc_co_u32_e32 v35, vcc, 0, v21, vcc
	v_add_co_u32_e32 v68, vcc, s13, v24
	s_mov_b32 s28, 0xe000
	s_nop 0
	v_addc_co_u32_e32 v69, vcc, 0, v25, vcc
	v_add_co_u32_e32 v74, vcc, s13, v22
	s_mov_b32 s47, 0x8000
	s_nop 0
	v_addc_co_u32_e32 v75, vcc, 0, v23, vcc
	global_load_dword v202, v[30:31], off
	global_load_dword v195, v[32:33], off
	global_load_dwordx2 v[76:77], v[34:35], off
	global_load_dword v215, v[68:69], off
	global_load_dword v194, v[74:75], off
	v_add_co_u32_e32 v74, vcc, s69, v20
	s_mov_b32 s24, 0
	s_nop 0
	v_addc_co_u32_e32 v75, vcc, 0, v21, vcc
	v_add_co_u32_e32 v84, vcc, s33, v82
	global_load_dword v225, v[26:27], off
	global_load_dword v199, v[28:29], off
	global_load_dwordx2 v[68:69], v[20:21], off
	global_load_dword v193, v[22:23], off
	global_load_dword v201, v[24:25], off
	s_nop 0
	v_addc_co_u32_e32 v85, vcc, 0, v83, vcc
	v_add_co_u32_e32 v86, vcc, s33, v80
	v_add_u32_e32 v217, s8, v175
	s_nop 0
	v_addc_co_u32_e32 v87, vcc, 0, v81, vcc
	v_add_co_u32_e32 v88, vcc, s3, v78
	s_mov_b32 s3, 0xa000
	s_nop 0
	v_addc_co_u32_e32 v89, vcc, 0, v79, vcc
	v_add_co_u32_e32 v92, vcc, s63, v82
	s_add_i32 s21, s8, 32
	s_nop 0
	v_addc_co_u32_e32 v93, vcc, 0, v83, vcc
	v_add_co_u32_e32 v94, vcc, s63, v80
	s_sub_i32 s22, s17, 32
	s_nop 0
	v_addc_co_u32_e32 v95, vcc, 0, v81, vcc
	v_add_co_u32_e32 v90, vcc, s67, v78
	v_mov_b32_e32 v112, 0
	s_nop 0
	v_addc_co_u32_e32 v91, vcc, 0, v79, vcc
	v_add_co_u32_e32 v96, vcc, s10, v82
	v_mov_b32_e32 v113, 0
	s_nop 0
	v_addc_co_u32_e32 v97, vcc, 0, v83, vcc
	v_add_co_u32_e32 v98, vcc, s10, v80
	s_lshl_b32 s10, s0, 9
	s_nop 0
	v_addc_co_u32_e32 v99, vcc, 0, v81, vcc
	v_add_co_u32_e32 v100, vcc, s9, v78
	s_mov_b32 s9, 1
	s_nop 0
	v_addc_co_u32_e32 v101, vcc, 0, v79, vcc
	global_load_dwordx2 v[108:109], v[90:91], off
	global_load_dword v229, v[96:97], off
	global_load_dword v221, v[98:99], off
	s_nop 0
	global_load_dwordx2 v[90:91], v[100:101], off
	v_add_co_u32_e32 v96, vcc, s66, v82
	v_mov_b32_e32 v120, 0
	s_nop 0
	v_addc_co_u32_e32 v97, vcc, 0, v83, vcc
	v_add_co_u32_e32 v98, vcc, s66, v80
	v_mov_b32_e32 v121, 0
	s_nop 0
	v_addc_co_u32_e32 v99, vcc, 0, v81, vcc
	v_add_co_u32_e32 v100, vcc, s1, v78
	s_mov_b32 s1, s11
	s_nop 0
	v_addc_co_u32_e32 v101, vcc, 0, v79, vcc
	v_add_co_u32_e32 v102, vcc, s12, v82
	v_writelane_b32 v253, s0, 63
	s_nop 0
	v_addc_co_u32_e32 v103, vcc, 0, v83, vcc
	v_add_co_u32_e32 v104, vcc, s12, v80
	v_writelane_b32 v254, s1, 0
	s_nop 0
	v_addc_co_u32_e32 v105, vcc, 0, v81, vcc
	global_load_dword v231, v[96:97], off
	global_load_dword v223, v[98:99], off
	s_nop 0
	global_load_dwordx2 v[100:101], v[100:101], off
	s_nop 0
	global_load_dword v232, v[102:103], off
	global_load_dword v222, v[104:105], off
	v_add_co_u32_e32 v96, vcc, s63, v78
	v_mov_b32_e32 v124, 0
	s_nop 0
	v_addc_co_u32_e32 v97, vcc, 0, v79, vcc
	v_add_co_u32_e32 v98, vcc, s69, v82
	v_mov_b32_e32 v125, 0
	s_nop 0
	v_addc_co_u32_e32 v99, vcc, 0, v83, vcc
	v_add_co_u32_e32 v102, vcc, s69, v80
	v_mov_b32_e32 v110, 0
	s_nop 0
	v_addc_co_u32_e32 v103, vcc, 0, v81, vcc
	v_add_co_u32_e32 v104, vcc, s66, v78
	v_mov_b32_e32 v111, 0
	s_nop 0
	v_addc_co_u32_e32 v105, vcc, 0, v79, vcc
	global_load_dwordx2 v[114:115], v[96:97], off
	global_load_dword v234, v[98:99], off
	global_load_dword v226, v[102:103], off
	global_load_dwordx2 v[118:119], v[104:105], off
	v_add_co_u32_e32 v96, vcc, s13, v82
	v_mov_b32_e32 v116, 0
	s_nop 0
	v_addc_co_u32_e32 v97, vcc, 0, v83, vcc
	v_add_co_u32_e32 v98, vcc, s13, v80
	v_mov_b32_e32 v117, 0
	s_nop 0
	v_addc_co_u32_e32 v99, vcc, 0, v81, vcc
	v_add_co_u32_e32 v102, vcc, s69, v78
	v_mov_b32_e32 v122, 0
	s_nop 0
	v_addc_co_u32_e32 v103, vcc, 0, v79, vcc
	global_load_dword v235, v[96:97], off
	global_load_dword v227, v[98:99], off
	s_nop 0
	global_load_dwordx2 v[102:103], v[102:103], off
	s_nop 0
	global_load_dwordx2 v[104:105], v[74:75], off
	global_load_dword v237, v[84:85], off
	global_load_dword v230, v[86:87], off
	global_load_dword v224, v[80:81], off
	global_load_dword v233, v[82:83], off
	global_load_dwordx2 v[128:129], v[88:89], off
	global_load_dword v236, v[92:93], off
	global_load_dword v228, v[94:95], off
	global_load_dwordx2 v[106:107], v[78:79], off
	v_and_b32_e32 v80, 64, v208
	v_add_u32_e32 v74, 64, v80
	v_cmp_lt_i32_e32 vcc, v57, v74
	v_xor_b32_e32 v75, 2, v208
	v_add_u32_e32 v81, -16, v208
	v_cndmask_b32_e32 v57, v208, v57, vcc
	v_cmp_lt_i32_e32 vcc, v75, v74
	v_lshlrev_b32_e32 v57, 2, v57
	v_lshl_add_u64 v[78:79], v[38:39], 0, s[10:11]
	v_cndmask_b32_e32 v75, v208, v75, vcc
	v_lshlrev_b32_e32 v203, 2, v75
	v_xor_b32_e32 v75, 4, v208
	v_cmp_lt_i32_e32 vcc, v75, v74
	v_mov_b32_e32 v84, 0
	v_mov_b32_e32 v85, 0
	v_cndmask_b32_e32 v74, v208, v75, vcc
	v_cmp_lt_i32_e32 vcc, v81, v80
	v_lshlrev_b32_e32 v216, 2, v74
	v_lshl_add_u64 v[74:75], v[36:37], 0, s[10:11]
	v_cndmask_b32_e32 v81, v81, v208, vcc
	v_lshlrev_b32_e32 v218, 2, v81
	v_subrev_u32_e32 v81, 32, v208
	v_cmp_lt_i32_e32 vcc, v81, v80
	v_or_b32_e32 v80, v80, v0
	v_lshl_or_b32 v220, v80, 2, v209
	v_cndmask_b32_e32 v81, v81, v208, vcc
	v_lshlrev_b32_e32 v219, 2, v81
	v_mov_b32_e32 v80, 0
	v_mov_b32_e32 v81, 0
	v_mov_b32_e32 v88, 0
	v_mov_b32_e32 v89, 0
	v_mov_b32_e32 v94, 0
	v_mov_b32_e32 v95, 0
	v_mov_b32_e32 v98, 0
	v_mov_b32_e32 v99, 0
	v_mov_b32_e32 v82, 0
	v_mov_b32_e32 v83, 0
	v_mov_b32_e32 v86, 0
	v_mov_b32_e32 v87, 0
	v_mov_b32_e32 v92, 0
	v_mov_b32_e32 v93, 0
	v_mov_b32_e32 v96, 0
	v_mov_b32_e32 v97, 0
	v_mov_b32_e32 v123, 0
	v_mov_b32_e32 v126, 0
	v_mov_b32_e32 v127, 0
	s_mov_b32 s23, s17
	s_waitcnt vmcnt(0)
	s_branch .LBB0_291

.LBB0_295:
	s_min_i32 s1, s24, s20
	s_lshl_b32 s1, s1, 5
	s_sub_i32 s25, s17, s1
	s_waitcnt vmcnt(8)
	s_cmp_lt_u32 s24, 2
	s_cbranch_scc1 .Lscan_r1_skip0
	ds_write_b128 v180, v[4:7]
	ds_write_b128 v180, v[8:11] offset:256
	ds_read_b32 v224, v181
	ds_read_b32 v227, v181 offset:64
	ds_read_b32 v226, v181 offset:128
	ds_read_b32 v222, v181 offset:192
	ds_read_b32 v223, v181 offset:256
	ds_read_b32 v221, v181 offset:320
	ds_read_b32 v228, v181 offset:384
	ds_read_b32 v230, v181 offset:448
	s_waitcnt lgkmcnt(4)
	ds_write_b128 v180, v[12:15]
	ds_write_b128 v180, v[16:19] offset:256
	ds_read_b32 v233, v181
	ds_read_b32 v235, v181 offset:64
	ds_read_b32 v234, v181 offset:128
	ds_read_b32 v232, v181 offset:192
	ds_read_b32 v231, v181 offset:256
	ds_read_b32 v229, v181 offset:320
	ds_read_b32 v236, v181 offset:384
	ds_read_b32 v237, v181 offset:448
	s_waitcnt lgkmcnt(4)
	ds_write_b128 v180, v[20:23]
	ds_write_b128 v180, v[24:27] offset:256
	ds_read_b64 v[106:107], v182
	ds_read_b64 v[102:103], v182 offset:128
	ds_read_b64 v[118:119], v182 offset:256
	ds_read_b64 v[114:115], v182 offset:384
	s_waitcnt lgkmcnt(4)
	ds_write_b128 v180, v[28:31]
	ds_write_b128 v180, v[32:35] offset:256
	ds_read_b64 v[100:101], v182
	ds_read_b64 v[90:91], v182 offset:128
	ds_read_b64 v[108:109], v182 offset:256
	ds_read_b64 v[128:129], v182 offset:384
	s_waitcnt lgkmcnt(0)
.Lscan_r1_skip0:
	s_add_i32 s98, s24, 2
	s_min_i32 s98, s98, s20
	s_lshl_b32 s98, s98, 5
	s_add_i32 s98, s98, s96
	s_lshl_b32 s99, s98, 12
	s_add_i32 s99, s99, s97
	s_lshl_b32 s98, s98, 13
	s_add_i32 s98, s98, s97
	s_add_i32 s98, s98, s97
	v_add_u32_e32 v88, s99, v177
	v_add_u32_e32 v89, 0x4000, v88
	v_add_u32_e32 v116, s98, v178
	v_add_u32_e32 v117, 0x4000, v116
	v_add_u32_e32 v216, 0x8000, v116
	v_add_u32_e32 v217, 0xc000, v116
	global_load_dwordx4 v[4:7], v88, s[64:65]
	global_load_dwordx4 v[8:11], v89, s[64:65]
	global_load_dwordx4 v[12:15], v88, s[72:73]
	global_load_dwordx4 v[16:19], v89, s[72:73]
	global_load_dwordx4 v[20:23], v116, s[74:75]
	global_load_dwordx4 v[24:27], v117, s[74:75]
	global_load_dwordx4 v[28:31], v216, s[74:75]
	global_load_dwordx4 v[32:35], v217, s[74:75]
	s_cmp_gt_i32 s25, 31
	v_lshlrev_b32_e32 v168, 16, v232
	s_mov_b64 s[0:1], -1
	v_lshlrev_b32_e32 v170, 16, v234
	v_lshlrev_b32_e32 v166, 16, v231
	v_lshlrev_b32_e32 v158, 16, v229
	s_cbranch_scc1 .LBB0_297
	s_min_i32 s0, s25, 32
	v_add_f32_e32 v130, 0, v106
	v_cmp_gt_i32_e32 vcc, s0, v176
	v_and_b32_e32 v132, 0xffff0000, v235
	v_and_b32_e32 v134, 0xffff0000, v234
	v_cndmask_b32_e32 v136, 0, v130, vcc
	v_add_f32_e32 v130, 0, v107
	v_cndmask_b32_e32 v139, 0, v130, vcc
	v_lshlrev_b32_e32 v130, 16, v233
	v_cndmask_b32_e32 v131, 0, v130, vcc
	v_and_b32_e32 v130, 0xffff0000, v233
	v_cndmask_b32_e32 v241, 0, v130, vcc
	v_cmp_gt_i32_e32 vcc, s0, v1
	v_lshlrev_b32_e32 v130, 16, v235
	v_and_b32_e32 v135, 0xffff0000, v232
	v_cndmask_b32_e32 v133, 0, v102, vcc
	v_add_f32_e32 v138, v136, v133
	v_cndmask_b32_e32 v239, 0, v130, vcc
	v_cndmask_b32_e32 v240, 0, v132, vcc
	v_cndmask_b32_e32 v133, 0, v103, vcc
	v_cmp_gt_i32_e32 vcc, s0, v40
	v_and_b32_e32 v137, 0xffff0000, v231
	v_and_b32_e32 v140, 0xffff0000, v229
	v_cndmask_b32_e32 v132, 0, v118, vcc
	v_cmp_gt_i32_e32 vcc, s0, v41
	v_pk_add_f32 v[146:147], v[132:133], v[138:139]
	v_lshlrev_b32_e32 v159, 16, v236
	v_cndmask_b32_e32 v157, 0, v134, vcc
	v_cndmask_b32_e32 v156, 0, v170, vcc
	v_cndmask_b32_e32 v133, 0, v119, vcc
	v_cmp_gt_i32_e32 vcc, s0, v54
	v_lshlrev_b32_e32 v162, 16, v237
	v_and_b32_e32 v163, 0xffff0000, v236
	v_cndmask_b32_e32 v132, 0, v114, vcc
	v_cmp_gt_i32_e32 vcc, s0, v3
	v_pk_add_f32 v[148:149], v[132:133], v[146:147]
	s_nop 0
	v_cndmask_b32_e32 v155, 0, v135, vcc
	v_cndmask_b32_e32 v154, 0, v168, vcc
	v_cndmask_b32_e32 v133, 0, v115, vcc
	v_cmp_gt_i32_e32 vcc, s0, v52
	s_nop 1
	v_cndmask_b32_e32 v132, 0, v100, vcc
	v_cmp_gt_i32_e32 vcc, s0, v43
	v_pk_add_f32 v[142:143], v[132:133], v[148:149]
	s_nop 0
	v_cndmask_b32_e32 v153, 0, v137, vcc
	v_cndmask_b32_e32 v152, 0, v166, vcc
	v_cndmask_b32_e32 v133, 0, v101, vcc
	v_cmp_gt_i32_e32 vcc, s0, v42
	s_nop 1
	v_cndmask_b32_e32 v132, 0, v90, vcc
	v_cmp_gt_i32_e32 vcc, s0, v51
	v_pk_add_f32 v[144:145], v[132:133], v[142:143]
	s_nop 0
	v_cndmask_b32_e32 v151, 0, v140, vcc
	v_cndmask_b32_e32 v150, 0, v158, vcc
	v_cndmask_b32_e32 v133, 0, v91, vcc
	v_cmp_gt_i32_e32 vcc, s0, v50
	s_nop 1
	v_cndmask_b32_e32 v132, 0, v108, vcc
	v_cmp_gt_i32_e32 vcc, s0, v45
	v_cmp_gt_i32_e64 s[0:1], s0, v44
	v_pk_add_f32 v[140:141], v[132:133], v[144:145]
	v_cndmask_b32_e32 v133, 0, v109, vcc
	v_cndmask_b32_e64 v132, 0, v128, s[0:1]
	v_cndmask_b32_e32 v130, 0, v159, vcc
	v_pk_add_f32 v[134:135], v[132:133], v[140:141]
	v_cndmask_b32_e64 v132, 0, v129, s[0:1]
	v_and_b32_e32 v159, 0xffff0000, v237
	v_add_f32_e32 v137, v132, v135
	v_cndmask_b32_e32 v133, 0, v163, vcc
	v_cndmask_b32_e64 v132, 0, v162, s[0:1]
	v_cndmask_b32_e64 v238, 0, v159, s[0:1]
	s_mov_b64 s[0:1], 0

.LBB0_299:
	s_add_i32 s25, s24, 2
	s_min_i32 s0, s25, s20
	s_lshl_b32 s0, s0, 5
	v_lshlrev_b32_e32 v244, 16, v224
	v_and_b32_e32 v245, 0xffff0000, v224
	v_lshlrev_b32_e32 v246, 16, v227
	v_and_b32_e32 v247, 0xffff0000, v227
	v_lshlrev_b32_e32 v248, 16, v226
	v_and_b32_e32 v249, 0xffff0000, v226
	v_lshlrev_b32_e32 v172, 16, v222
	v_and_b32_e32 v173, 0xffff0000, v222
	v_lshlrev_b32_e32 v170, 16, v223
	v_and_b32_e32 v171, 0xffff0000, v223
	v_lshlrev_b32_e32 v168, 16, v221
	v_and_b32_e32 v169, 0xffff0000, v221
	v_lshlrev_b32_e32 v166, 16, v228
	v_and_b32_e32 v167, 0xffff0000, v228
	s_ashr_i32 s1, s0, 31
	ds_bpermute_b32 v74, v218, v134
	ds_bpermute_b32 v75, v218, v137
	v_lshlrev_b32_e32 v158, 16, v230
	v_and_b32_e32 v159, 0xffff0000, v230
	s_waitcnt lgkmcnt(1)
	v_add_f32_e32 v78, v134, v74
	s_waitcnt lgkmcnt(0)
	v_add_f32_e32 v79, v137, v75
	v_cndmask_b32_e64 v162, v78, v134, s[40:41]
	v_cndmask_b32_e64 v163, v79, v137, s[40:41]
	s_nop 0
	ds_bpermute_b32 v242, v219, v162
	ds_bpermute_b32 v243, v219, v163
	s_waitcnt lgkmcnt(1)
	v_add_f32_e32 v242, v162, v242
	s_waitcnt lgkmcnt(0)
	v_add_f32_e32 v243, v163, v243
	v_cndmask_b32_e64 v162, v162, v242, s[42:43]
	v_cndmask_b32_e64 v243, v163, v243, s[42:43]
	v_sub_f32_e32 v250, v162, v134
	v_sub_f32_e32 v211, v243, v137
	v_add_f32_e32 v207, v136, v250
	v_add_f32_e32 v139, v139, v211
	ds_bpermute_b32 v242, v220, v162
	v_exp_f32_e32 v162, v207
	v_exp_f32_e32 v163, v139
	v_exp_f32_e64 v207, -v207
	v_exp_f32_e64 v139, -v139
	v_add_f32_e32 v147, v147, v211
	v_pk_mul_f32 v[162:163], v[162:163], v[244:245]
	v_mul_f32_e32 v131, v131, v207
	v_add_f32_e32 v207, v138, v250
	v_cvt_pk_bf16_f32 v162, v162, v163
	v_mul_f32_e32 v163, v241, v139
	v_exp_f32_e32 v138, v207
	v_exp_f32_e32 v139, v147
	v_cvt_pk_bf16_f32 v163, v131, v163
	v_exp_f32_e64 v131, -v207
	v_exp_f32_e64 v147, -v147
	v_pk_mul_f32 v[138:139], v[138:139], v[246:247]
	v_add_f32_e32 v146, v146, v250
	v_cvt_pk_bf16_f32 v138, v138, v139
	v_mul_f32_e32 v131, v239, v131
	v_mul_f32_e32 v139, v240, v147
	v_add_f32_e32 v147, v149, v211
	v_cvt_pk_bf16_f32 v207, v131, v139
	ds_write2_b32 v49, v162, v138 offset1:66
	v_exp_f32_e32 v138, v146
	v_exp_f32_e32 v139, v147
	v_exp_f32_e64 v146, -v146
	v_exp_f32_e64 v147, -v147
	v_add_u32_e32 v131, 0x2000, v49
	v_pk_mul_f32 v[138:139], v[138:139], v[248:249]
	v_add_f32_e32 v148, v148, v250
	v_add_f32_e32 v143, v143, v211
	ds_write2_b32 v131, v163, v207 offset0:64 offset1:130
	v_cvt_pk_bf16_f32 v131, v138, v139
	v_pk_mul_f32 v[138:139], v[156:157], v[146:147]
	v_exp_f32_e32 v146, v148
	v_exp_f32_e32 v147, v143
	v_exp_f32_e64 v148, -v148
	v_exp_f32_e64 v149, -v143
	v_cvt_pk_bf16_f32 v156, v138, v139
	v_pk_mul_f32 v[138:139], v[146:147], v[172:173]
	v_add_f32_e32 v142, v142, v250
	v_cvt_pk_bf16_f32 v143, v138, v139
	v_pk_mul_f32 v[138:139], v[154:155], v[148:149]
	ds_write2_b32 v49, v131, v143 offset0:132 offset1:198
	v_add_f32_e32 v143, v145, v211
	v_cvt_pk_bf16_f32 v146, v138, v139
	v_exp_f32_e32 v138, v142
	v_exp_f32_e32 v139, v143
	v_exp_f32_e64 v142, -v142
	v_exp_f32_e64 v143, -v143
	v_add_u32_e32 v131, 0x2200, v49
	v_pk_mul_f32 v[138:139], v[138:139], v[170:171]
	v_add_f32_e32 v144, v144, v250
	v_add_f32_e32 v141, v141, v211
	ds_write2_b32 v131, v156, v146 offset0:68 offset1:134
	v_cvt_pk_bf16_f32 v131, v138, v139
	v_pk_mul_f32 v[138:139], v[152:153], v[142:143]
	v_exp_f32_e32 v142, v144
	v_exp_f32_e32 v143, v141
	v_exp_f32_e64 v144, -v144
	v_exp_f32_e64 v145, -v141
	v_cvt_pk_bf16_f32 v147, v138, v139
	v_pk_mul_f32 v[138:139], v[142:143], v[168:169]
	v_add_u32_e32 v143, 0x400, v49
	v_cvt_pk_bf16_f32 v141, v138, v139
	v_pk_mul_f32 v[138:139], v[150:151], v[144:145]
	v_add_f32_e32 v140, v140, v250
	v_add_f32_e32 v135, v135, v211
	v_cvt_pk_bf16_f32 v142, v138, v139
	ds_write2_b32 v143, v131, v141 offset0:8 offset1:74
	v_exp_f32_e32 v138, v140
	v_exp_f32_e32 v139, v135
	v_exp_f32_e64 v140, -v140
	v_exp_f32_e64 v141, -v135
	v_add_u32_e32 v131, 0x2400, v49
	ds_write2_b32 v131, v147, v142 offset0:72 offset1:138
	v_mov_b32_e32 v131, v133
	v_pk_mul_f32 v[138:139], v[138:139], v[166:167]
	v_pk_mul_f32 v[130:131], v[130:131], v[140:141]
	v_add_f32_e32 v133, v134, v250
	v_add_f32_e32 v137, v137, v211
	v_cvt_pk_bf16_f32 v138, v138, v139
	v_exp_f32_e32 v134, v133
	v_exp_f32_e32 v135, v137
	v_cvt_pk_bf16_f32 v139, v130, v131
	v_exp_f32_e64 v130, -v133
	v_exp_f32_e64 v131, -v137
	ds_bpermute_b32 v136, v220, v243
	v_mov_b32_e32 v133, v238
	v_pk_mul_f32 v[134:135], v[134:135], v[158:159]
	v_pk_mul_f32 v[130:131], v[132:133], v[130:131]
	v_cvt_pk_bf16_f32 v134, v134, v135
	v_cvt_pk_bf16_f32 v135, v130, v131
	v_add_u32_e32 v130, 0x2600, v49
	ds_write2_b32 v143, v138, v134 offset0:140 offset1:206
	ds_write2_b32 v130, v139, v135 offset0:76 offset1:142
	v_perm_b32 v130, v207, v163, s71
	v_perm_b32 v131, v146, v156, s71
	v_perm_b32 v132, v142, v147, s71
	v_perm_b32 v133, v135, v139, s71
	v_add_u32_e32 v134, v185, v179
	ds_write_b128 v134, v[130:133] offset:16896
	v_perm_b32 v130, v207, v163, s62
	v_perm_b32 v131, v146, v156, s62
	v_perm_b32 v132, v142, v147, s62
	v_perm_b32 v133, v135, v139, s62
	ds_write_b128 v134, v[130:133] offset:16976
	s_and_saveexec_b64 s[0:1], s[40:41]
	s_cbranch_execz .LBB0_301
	s_waitcnt lgkmcnt(11)
	v_exp_f32_e32 v130, v242
	s_waitcnt lgkmcnt(4)
	v_exp_f32_e32 v131, v136
	ds_write_b64 v187, v[130:131] offset:27136

.LBB0_305:
	s_add_i32 s10, s24, 1
	s_min_i32 s10, s10, s20
	s_lshl_b32 s10, s10, 5
	s_mov_b64 s[0:1], -1
	s_waitcnt vmcnt(8)
	s_cmp_lt_u32 s24, 2
	s_cbranch_scc1 .Lscan_r1_skip1
	ds_write_b128 v180, v[36:39] offset:27648
	ds_write_b128 v180, v[124:127] offset:27904
	ds_read_b32 v193, v181 offset:27648
	ds_read_b32 v194, v181 offset:27712
	ds_read_b32 v195, v181 offset:27776
	ds_read_b32 v191, v181 offset:27840
	ds_read_b32 v190, v181 offset:27904
	ds_read_b32 v192, v181 offset:27968
	ds_read_b32 v189, v181 offset:28032
	ds_read_b32 v199, v181 offset:28096
	s_waitcnt lgkmcnt(4)
	ds_write_b128 v180, v[80:83] offset:27648
	ds_write_b128 v180, v[84:87] offset:27904
	ds_read_b32 v201, v181 offset:27648
	ds_read_b32 v215, v181 offset:27712
	ds_read_b32 v202, v181 offset:27776
	ds_read_b32 v200, v181 offset:27840
	ds_read_b32 v197, v181 offset:27904
	ds_read_b32 v198, v181 offset:27968
	ds_read_b32 v196, v181 offset:28032
	ds_read_b32 v225, v181 offset:28096
	s_waitcnt lgkmcnt(4)
	ds_write_b128 v180, v[92:95] offset:27648
	ds_write_b128 v180, v[96:99] offset:27904
	ds_read_b64 v[68:69], v182 offset:27648
	ds_read_b64 v[104:105], v182 offset:27776
	ds_read_b64 v[76:77], v182 offset:27904
	ds_read_b64 v[72:73], v182 offset:28032
	s_waitcnt lgkmcnt(4)
	ds_write_b128 v180, v[110:113] offset:27648
	ds_write_b128 v180, v[120:123] offset:27904
	ds_read_b64 v[70:71], v182 offset:27648
	ds_read_b64 v[62:63], v182 offset:27776
	ds_read_b64 v[66:67], v182 offset:27904
	ds_read_b64 v[64:65], v182 offset:28032
	s_waitcnt lgkmcnt(0)
.Lscan_r1_skip1:
	s_add_i32 s98, s24, 3
	s_min_i32 s98, s98, s20
	s_lshl_b32 s98, s98, 5
	s_add_i32 s98, s98, s96
	s_lshl_b32 s99, s98, 12
	s_add_i32 s99, s99, s97
	s_lshl_b32 s98, s98, 13
	s_add_i32 s98, s98, s97
	s_add_i32 s98, s98, s97
	v_add_u32_e32 v88, s99, v177
	v_add_u32_e32 v89, 0x4000, v88
	v_add_u32_e32 v116, s98, v178
	v_add_u32_e32 v117, 0x4000, v116
	v_add_u32_e32 v216, 0x8000, v116
	v_add_u32_e32 v217, 0xc000, v116
	global_load_dwordx4 v[36:39], v88, s[64:65]
	global_load_dwordx4 v[124:127], v89, s[64:65]
	global_load_dwordx4 v[80:83], v88, s[72:73]
	global_load_dwordx4 v[84:87], v89, s[72:73]
	global_load_dwordx4 v[92:95], v116, s[74:75]
	global_load_dwordx4 v[96:99], v117, s[74:75]
	global_load_dwordx4 v[110:113], v216, s[74:75]
	global_load_dwordx4 v[120:123], v217, s[74:75]
	s_sub_i32 s10, s17, s10
	s_cmp_gt_i32 s10, 31
	s_cbranch_scc1 .LBB0_307
	s_min_i32 s10, s10, 32
	v_add_f32_e32 v130, 0, v68
	v_cmp_gt_i32_e32 vcc, s10, v176
	v_cmp_gt_i32_e64 s[0:1], s10, v40
	v_and_b32_e32 v133, 0xffff0000, v215
	v_cndmask_b32_e32 v144, 0, v130, vcc
	v_add_f32_e32 v130, 0, v69
	v_cndmask_b32_e32 v143, 0, v130, vcc
	v_lshlrev_b32_e32 v130, 16, v201
	v_cndmask_b32_e32 v141, 0, v130, vcc
	v_and_b32_e32 v130, 0xffff0000, v201
	v_cndmask_b32_e32 v169, 0, v130, vcc
	v_cmp_gt_i32_e32 vcc, s10, v1
	v_lshlrev_b32_e32 v132, 16, v202
	v_cndmask_b32_e64 v138, 0, v132, s[0:1]
	v_cndmask_b32_e32 v130, 0, v104, vcc
	v_add_f32_e32 v142, v144, v130
	v_lshlrev_b32_e32 v130, 16, v215
	v_cndmask_b32_e32 v140, 0, v130, vcc
	v_cndmask_b32_e32 v131, 0, v105, vcc
	v_cndmask_b32_e64 v130, 0, v76, s[0:1]
	v_pk_add_f32 v[146:147], v[130:131], v[142:143]
	v_cndmask_b32_e64 v130, 0, v77, s[0:1]
	v_add_f32_e32 v241, v130, v147
	v_cndmask_b32_e32 v139, 0, v133, vcc
	v_and_b32_e32 v130, 0xffff0000, v202
	v_cmp_gt_i32_e32 vcc, s10, v3
	v_cndmask_b32_e64 v166, 0, v130, s[0:1]
	v_and_b32_e32 v131, 0xffff0000, v197
	v_cndmask_b32_e32 v130, 0, v72, vcc
	v_add_f32_e32 v239, v130, v146
	v_cndmask_b32_e32 v130, 0, v73, vcc
	v_add_f32_e32 v240, v130, v241
	v_lshlrev_b32_e32 v130, 16, v200
	v_cndmask_b32_e32 v135, 0, v130, vcc
	v_and_b32_e32 v130, 0xffff0000, v200
	v_cndmask_b32_e32 v159, 0, v130, vcc
	v_cmp_gt_i32_e32 vcc, s10, v43
	v_cmp_gt_i32_e64 s[0:1], s10, v42
	v_and_b32_e32 v133, 0xffff0000, v196
	v_cndmask_b32_e32 v130, 0, v70, vcc
	v_add_f32_e32 v173, v130, v239
	v_cndmask_b32_e32 v130, 0, v71, vcc
	v_add_f32_e32 v238, v130, v240
	v_lshlrev_b32_e32 v130, 16, v197
	v_cndmask_b32_e32 v134, 0, v130, vcc
	v_lshlrev_b32_e32 v130, 16, v198
	v_cndmask_b32_e64 v132, 0, v62, s[0:1]
	v_cndmask_b32_e32 v137, 0, v131, vcc
	v_cndmask_b32_e64 v136, 0, v130, s[0:1]
	v_and_b32_e32 v130, 0xffff0000, v198
	v_cmp_gt_i32_e32 vcc, s10, v45
	v_add_f32_e32 v171, v132, v173
	v_cndmask_b32_e64 v132, 0, v63, s[0:1]
	v_cndmask_b32_e64 v131, 0, v130, s[0:1]
	v_cndmask_b32_e32 v130, 0, v66, vcc
	v_add_f32_e32 v172, v132, v238
	v_add_f32_e32 v168, v130, v171
	v_cndmask_b32_e32 v130, 0, v67, vcc
	v_cmp_gt_i32_e64 s[0:1], s10, v44
	v_add_f32_e32 v170, v130, v172
	v_lshlrev_b32_e32 v130, 16, v196
	v_cndmask_b32_e64 v148, 0, v65, s[0:1]
	v_lshlrev_b32_e32 v132, 16, v225
	v_cndmask_b32_e64 v145, 0, v64, s[0:1]
	v_add_f32_e32 v167, v148, v170
	v_and_b32_e32 v148, 0xffff0000, v225
	v_cndmask_b32_e32 v130, 0, v130, vcc
	v_add_f32_e32 v145, v145, v168
	v_cndmask_b32_e32 v133, 0, v133, vcc
	v_cndmask_b32_e64 v132, 0, v132, s[0:1]
	v_cndmask_b32_e64 v158, 0, v148, s[0:1]
	s_mov_b64 s[0:1], 0

.LBB0_309:
	s_add_i32 s0, s24, 3
	s_min_i32 s0, s0, s20
	s_lshl_b32 s0, s0, 5
	v_lshlrev_b32_e32 v162, 16, v193
	v_and_b32_e32 v163, 0xffff0000, v193
	v_lshlrev_b32_e32 v244, 16, v194
	v_and_b32_e32 v245, 0xffff0000, v194
	v_lshlrev_b32_e32 v246, 16, v195
	v_and_b32_e32 v247, 0xffff0000, v195
	v_lshlrev_b32_e32 v156, 16, v191
	v_and_b32_e32 v157, 0xffff0000, v191
	v_lshlrev_b32_e32 v154, 16, v190
	v_and_b32_e32 v155, 0xffff0000, v190
	v_lshlrev_b32_e32 v152, 16, v192
	v_and_b32_e32 v153, 0xffff0000, v192
	v_lshlrev_b32_e32 v150, 16, v189
	v_and_b32_e32 v151, 0xffff0000, v189
	s_ashr_i32 s1, s0, 31
	ds_bpermute_b32 v74, v218, v145
	ds_bpermute_b32 v75, v218, v167
	v_lshlrev_b32_e32 v148, 16, v199
	v_and_b32_e32 v149, 0xffff0000, v199
	s_waitcnt lgkmcnt(1)
	v_add_f32_e32 v78, v145, v74
	s_waitcnt lgkmcnt(0)
	v_add_f32_e32 v79, v167, v75
	v_cndmask_b32_e64 v207, v78, v145, s[40:41]
	v_cndmask_b32_e64 v211, v79, v167, s[40:41]
	s_nop 0
	ds_bpermute_b32 v242, v219, v207
	ds_bpermute_b32 v243, v219, v211
	s_waitcnt lgkmcnt(1)
	v_add_f32_e32 v242, v207, v242
	s_waitcnt lgkmcnt(0)
	v_add_f32_e32 v243, v211, v243
	v_cndmask_b32_e64 v207, v207, v242, s[42:43]
	v_cndmask_b32_e64 v211, v211, v243, s[42:43]
	ds_bpermute_b32 v242, v220, v207
	v_sub_f32_e32 v207, v207, v145
	v_sub_f32_e32 v243, v211, v167
	v_add_f32_e32 v144, v144, v207
	v_add_f32_e32 v250, v143, v243
	v_exp_f32_e32 v248, v144
	ds_bpermute_b32 v143, v220, v211
	v_exp_f32_e64 v144, -v144
	v_exp_f32_e64 v211, -v250
	v_exp_f32_e32 v249, v250
	v_mul_f32_e32 v141, v141, v144
	v_mul_f32_e32 v144, v169, v211
	v_pk_mul_f32 v[162:163], v[248:249], v[162:163]
	v_cvt_pk_bf16_f32 v144, v141, v144
	v_add_f32_e32 v141, v142, v207
	v_add_f32_e32 v142, v147, v243
	v_cvt_pk_bf16_f32 v250, v162, v163
	v_exp_f32_e32 v162, v141
	v_exp_f32_e32 v163, v142
	v_exp_f32_e64 v248, -v141
	v_exp_f32_e64 v249, -v142
	v_add_u32_e32 v169, v46, v184
	v_pk_mul_f32 v[162:163], v[162:163], v[244:245]
	v_mov_b32_e32 v141, v139
	v_cvt_pk_bf16_f32 v142, v162, v163
	v_add_u32_e32 v163, 0x6c00, v169
	v_pk_mul_f32 v[140:141], v[140:141], v[248:249]
	ds_write2_b32 v163, v250, v142 offset1:66
	v_add_f32_e32 v142, v146, v207
	v_add_f32_e32 v147, v241, v243
	v_cvt_pk_bf16_f32 v162, v140, v141
	v_exp_f32_e32 v140, v142
	v_exp_f32_e32 v141, v147
	v_exp_f32_e64 v146, -v142
	v_exp_f32_e64 v147, -v147
	v_add_u32_e32 v139, 0x8c00, v169
	ds_write2_b32 v139, v144, v162 offset0:64 offset1:130
	v_mov_b32_e32 v139, v166
	v_pk_mul_f32 v[140:141], v[140:141], v[246:247]
	v_pk_mul_f32 v[138:139], v[138:139], v[146:147]
	v_add_f32_e32 v146, v239, v207
	v_add_f32_e32 v147, v240, v243
	v_cvt_pk_bf16_f32 v142, v140, v141
	v_exp_f32_e32 v140, v146
	v_exp_f32_e32 v141, v147
	v_exp_f32_e64 v146, -v146
	v_exp_f32_e64 v147, -v147
	v_cvt_pk_bf16_f32 v166, v138, v139
	v_pk_mul_f32 v[138:139], v[140:141], v[156:157]
	v_mul_f32_e32 v135, v135, v146
	v_cvt_pk_bf16_f32 v138, v138, v139
	v_mul_f32_e32 v139, v159, v147
	v_add_f32_e32 v140, v173, v207
	v_add_f32_e32 v141, v238, v243
	v_cvt_pk_bf16_f32 v146, v135, v139
	ds_write2_b32 v163, v142, v138 offset0:132 offset1:198
	v_exp_f32_e32 v138, v140
	v_exp_f32_e32 v139, v141
	v_exp_f32_e64 v140, -v140
	v_exp_f32_e64 v141, -v141
	v_add_u32_e32 v135, 0x8e00, v169
	ds_write2_b32 v135, v166, v146 offset0:68 offset1:134
	v_mov_b32_e32 v135, v137
	v_pk_mul_f32 v[138:139], v[138:139], v[154:155]
	v_pk_mul_f32 v[134:135], v[134:135], v[140:141]
	v_add_f32_e32 v137, v171, v207
	v_add_f32_e32 v140, v172, v243
	v_cvt_pk_bf16_f32 v142, v138, v139
	v_exp_f32_e32 v138, v137
	v_exp_f32_e32 v139, v140
	v_cvt_pk_bf16_f32 v141, v134, v135
	v_exp_f32_e64 v134, -v137
	v_exp_f32_e64 v135, -v140
	v_mov_b32_e32 v137, v131
	v_pk_mul_f32 v[138:139], v[138:139], v[152:153]
	v_add_u32_e32 v131, 0x9000, v169
	v_pk_mul_f32 v[134:135], v[136:137], v[134:135]
	v_add_f32_e32 v136, v168, v207
	v_add_f32_e32 v137, v170, v243
	v_cvt_pk_bf16_f32 v138, v138, v139
	v_cvt_pk_bf16_f32 v139, v134, v135
	v_exp_f32_e32 v134, v136
	v_exp_f32_e32 v135, v137
	v_exp_f32_e64 v136, -v136
	v_exp_f32_e64 v137, -v137
	ds_write2_b32 v131, v141, v139 offset0:72 offset1:138
	v_mov_b32_e32 v131, v133
	v_add_u32_e32 v140, 0x7000, v169
	v_pk_mul_f32 v[134:135], v[134:135], v[150:151]
	v_pk_mul_f32 v[130:131], v[130:131], v[136:137]
	v_add_f32_e32 v133, v145, v207
	v_add_f32_e32 v136, v167, v243
	ds_write2_b32 v140, v142, v138 offset0:8 offset1:74
	v_cvt_pk_bf16_f32 v138, v134, v135
	v_exp_f32_e32 v134, v133
	v_exp_f32_e32 v135, v136
	v_cvt_pk_bf16_f32 v137, v130, v131
	v_exp_f32_e64 v130, -v133
	v_exp_f32_e64 v131, -v136
	v_mov_b32_e32 v133, v158
	v_pk_mul_f32 v[134:135], v[134:135], v[148:149]
	v_pk_mul_f32 v[130:131], v[132:133], v[130:131]
	v_cvt_pk_bf16_f32 v134, v134, v135
	v_cvt_pk_bf16_f32 v135, v130, v131
	v_add_u32_e32 v130, 0x9200, v169
	ds_write2_b32 v140, v138, v134 offset0:140 offset1:206
	ds_write2_b32 v130, v137, v135 offset0:76 offset1:142
	v_perm_b32 v130, v162, v144, s71
	v_perm_b32 v131, v146, v166, s71
	v_perm_b32 v132, v139, v141, s71
	v_perm_b32 v133, v135, v137, s71
	v_add_u32_e32 v134, v48, v179
	ds_write_b128 v134, v[130:133] offset:44544
	v_perm_b32 v130, v162, v144, s62
	v_perm_b32 v131, v146, v166, s62
	v_perm_b32 v132, v139, v141, s62
	v_perm_b32 v133, v135, v137, s62
	ds_write_b128 v134, v[130:133] offset:44624
	s_and_saveexec_b64 s[0:1], s[40:41]
	s_cbranch_execz .LBB0_290
	s_waitcnt lgkmcnt(11)
	v_exp_f32_e32 v130, v242
	s_waitcnt lgkmcnt(10)
	v_exp_f32_e32 v131, v143
	v_add_u32_e32 v132, v48, v186
	ds_write_b64 v132, v[130:131] offset:54784
	s_branch .LBB0_290
